# RG-LRU gate GEMM: block-diagonal weight, the two all-zero K tiles of every output tile are skipped (one K-loop iteration instead of two; exact)
# speedup vs baseline: 1.0142x; 1.0061x over previous
;     __device__ __forceinline__ const char* abase(const Gemm& g, const Unit& u, size_t tstepA) const { return (const char*)g.A + (size_t)u.pm * tstepA; }
;     __device__ __forceinline__ const char* bbase(const Gemm& g, const Unit& u, size_t tstepB) const { return (const char*)g.Bt + (size_t)u.pn * tstepB; }
;     __device__ __forceinline__ bool next(int i, Unit& u) const { if (!base.next(i >> 2, u)) return false; u.kind = i & 3; return true; }
;     __device__ __forceinline__ const char* abase(const Gemm&, const Unit& u, size_t tstepA) const { return (const char*)(u.kind == 3 ? Cat : Hx) + (size_t)u.pm * tstepA; }
; #define PG8_WAIT_V(n) asm volatile("s_waitcnt vmcnt(" #n ")" ::: "memory")
; #define PG8_BAR __builtin_amdgcn_s_barrier()
; template <class Epi, class Sched>
; __device__ __forceinline__ void gemm_phase(LAS unsigned char* lds, const Gemm g, const Sched& S, const Epi& E) {
;     ...
;     for (int i = 0; i < 2; ++i) { int R, C; stage_rc(tid * 16 + i * 8192, R, C); const int Rb = Epi::PERM ? ((R & ~31) + perm32(R & 31)) : R;
;         voffA[i] = (unsigned)(R * g.lda + C) * 2u; voffB[i] = (unsigned)(Rb * g.ldb + C) * 2u; }
;     const size_t kstep = (size_t)(BK * 2);
;     const size_t hstepA = (size_t)HALF * g.lda * 2, hstepB = (size_t)HALF * g.ldb * 2;
;     const size_t tstepA = 2 * hstepA, tstepB = 2 * hstepB;
;     const unsigned ldsw = (unsigned)wid * 1024u;
;     const int aoff = lds_byte(wr * 64 + fr, fq * 8), boff = lds_byte(wc * 32 + fr, fq * 8);
;     ...
;     Unit cur, nxt; int ui = 0;
;     if (!S.next(0, cur)) return;
;     Acc acc;
; #pragma unroll
;     for (int a = 0; a < 2; ++a)
; #pragma unroll
;         for (int b = 0; b < 2; ++b)
; #pragma unroll
;             for (int m = 0; m < 4; ++m)
; #pragma unroll
;                 for (int n = 0; n < 2; ++n) acc[a][b][m][n] = (f32x4){0.f, 0.f, 0.f, 0.f};
;     bf16x8 At[4][2], B0[2][2], B1[2][2];
;     const char* cA = S.abase(g, cur, tstepA); const char* cB = S.bbase(g, cur, tstepB);
;     PG8_STAGE(PG8_SB(0, 0), cB, voffB); PG8_STAGE(PG8_SB(0, 1), cB + hstepB, voffB); PG8_STAGE(PG8_SA(0, 0), cA, voffA); PG8_STAGE(PG8_SA(0, 1), cA + hstepA, voffA);
;     if (wr == 1) PG8_BAR;
;     PG8_WAIT_V(2); PG8_BAR;
;     PG8_STAGE(PG8_SB(1, 0), cB + kstep, voffB); PG8_STAGE(PG8_SA(1, 0), cA + kstep, voffA); PG8_STAGE(PG8_SB(1, 1), cB + hstepB + kstep, voffB);
;     PG8_WAIT_V(6); PG8_BAR;
.LBB0_538:
	v_ashrrev_i32_e32 v0, 31, v10
	v_lshrrev_b32_e32 v0, 26, v0
	v_add_u32_e32 v0, v10, v0
	v_ashrrev_i32_e32 v11, 6, v0
	v_bfe_i32 v0, v10, 27, 1
	v_lshlrev_b32_e32 v2, 4, v10
	v_lshrrev_b32_e32 v0, 22, v0
	v_add_u32_e32 v0, v2, v0
	v_and_b32_e32 v0, 0xfffffc00, v0
	v_sub_u32_e32 v0, v2, v0
	s_waitcnt lgkmcnt(0)
	v_lshrrev_b32_e32 v3, 4, v0
	v_bitop3_b32 v0, v3, v0, 32 bitop3:0x6c
	v_ashrrev_i32_e32 v4, 31, v0
	v_lshrrev_b32_e32 v4, 26, v4
	v_add_u32_e32 v4, v0, v4
	v_lshlrev_b32_e32 v3, 3, v11
	v_ashrrev_i32_e32 v12, 6, v4
	v_and_b32_e32 v4, 0xc0, v4
	v_and_b32_e32 v3, -16, v3
	v_sub_u32_e32 v0, v0, v4
	v_add_u32_e32 v3, v12, v3
	v_ashrrev_i16_sdwa v0, v252, sext(v0) dst_sel:DWORD dst_unused:UNUSED_PAD src0_sel:DWORD src1_sel:BYTE_0
	v_lshlrev_b32_e32 v5, 5, v11
	v_bfe_i32 v13, v0, 0, 16
	v_lshlrev_b32_e32 v0, 1, v3
	v_lshrrev_b32_e32 v4, 2, v3
	v_and_b32_e32 v6, 3, v12
	s_mov_b32 s1, 0x7fffe0
	v_and_b32_e32 v5, 32, v5
	v_and_b32_e32 v0, 24, v0
	v_and_b32_e32 v4, 4, v4
	v_and_or_b32 v6, v3, s1, v6
	v_or3_b32 v0, v6, v4, v0
	v_add_lshl_u32 v4, v5, v13, 1
	v_add_u32_e32 v2, 0x2000, v2
	v_lshl_add_u32 v196, v3, 9, v4
	v_ashrrev_i32_e32 v3, 31, v2
	v_lshrrev_b32_e32 v3, 22, v3
	v_add_u32_e32 v3, v2, v3
	v_ashrrev_i32_e32 v14, 10, v3
	v_mul_i32_i24_e32 v3, 0x400, v14
	v_sub_u32_e32 v2, v2, v3
	v_lshrrev_b32_e32 v3, 4, v2
	v_bitop3_b32 v2, v3, v2, 32 bitop3:0x6c
	v_lshl_add_u32 v0, v0, 9, v4
	v_ashrrev_i32_e32 v4, 31, v2
	v_lshrrev_b32_e32 v4, 26, v4
	s_ashr_i32 s0, s13, 3
	v_lshlrev_b32_e32 v3, 3, v14
	v_add_u32_e32 v4, v2, v4
	s_add_u32 s13, s50, 0xb90000
	v_and_b32_e32 v3, -16, v3
	v_ashrrev_i32_e32 v15, 6, v4
	s_addc_u32 s44, s51, 0
	v_add_u32_e32 v3, v15, v3
	v_and_b32_e32 v6, 3, v15
	s_add_i32 s0, s14, s0
	v_and_or_b32 v6, v3, s1, v6
	s_ashr_i32 s1, s0, 31
	s_lshr_b32 s1, s1, 28
	s_add_i32 s1, s0, s1
	s_ashr_i32 s14, s1, 4
	s_and_b32 s1, s1, 0xfff0
	s_sub_i32 s0, s0, s1
	s_bfe_i32 s1, s0, 0x80000
	s_bfe_u32 s1, s1, 0x3000c
	s_add_i32 s1, s0, s1
	s_bfe_i32 s20, s1, 0x80000
	s_and_b32 s1, s1, 0xf8
	s_sub_i32 s0, s0, s1
	s_lshl_b32 s14, s14, 3
	s_sext_i32_i16 s20, s20
	s_sext_i32_i8 s0, s0
	s_lshr_b32 s24, s20, 3
	s_add_i32 s40, s14, s0
	v_and_b32_e32 v4, 0xc0, v4
	s_ashr_i32 s19, s15, 6
	s_ashr_i32 s41, s40, 31
	s_bfe_i64 s[20:21], s[24:25], 0x100000
	s_ashr_i32 s17, s15, 8
	v_sub_u32_e32 v2, v2, v4
	s_lshl_b32 s45, s19, 10
	s_lshl_b64 s[0:1], s[40:41], 17
	s_lshl_b64 s[20:21], s[20:21], 17
	s_lshr_b32 s48, s20, 9
	s_cmpk_lg_i32 s35, 0x100
	s_cselect_b32 s48, 0, s48
	v_ashrrev_i16_sdwa v2, v252, sext(v2) dst_sel:DWORD dst_unused:UNUSED_PAD src0_sel:DWORD src1_sel:BYTE_0
	s_add_u32 s20, s13, s20
	v_lshlrev_b32_e32 v5, 5, v14
	v_bfe_i32 v16, v2, 0, 16
	v_lshlrev_b32_e32 v2, 1, v3
	v_lshrrev_b32_e32 v4, 2, v3
	s_addc_u32 s21, s44, s21
	s_add_u32 s20, s20, s48
	s_addc_u32 s21, s21, 0
	s_add_i32 s46, s45, 0
	v_and_b32_e32 v5, 32, v5
	v_and_b32_e32 v2, 24, v2
	v_and_b32_e32 v4, 4, v4
	s_add_i32 m0, s46, 0x10000
	v_or3_b32 v2, v6, v4, v2
	v_add_lshl_u32 v4, v5, v16, 1
	global_load_lds_dwordx4 v0, s[20:21]
	s_add_i32 m0, s46, 0x12000
	v_lshl_add_u32 v200, v2, 9, v4
	s_add_u32 s30, s20, 0x10000
	global_load_lds_dwordx4 v200, s[20:21]
	s_addc_u32 s31, s21, 0
	s_add_i32 m0, s46, 0x14000
	v_lshl_add_u32 v198, v3, 9, v4
	global_load_lds_dwordx4 v0, s[30:31]
	s_add_i32 m0, s46, 0x16000
	s_add_u32 s0, s4, s0
	s_addc_u32 s1, s5, s1
	s_add_u32 s0, s0, s48
	s_addc_u32 s1, s1, 0
	s_add_i32 s47, s46, 0x2000
	global_load_lds_dwordx4 v200, s[30:31]
	s_mov_b32 m0, s46
	s_add_u32 s30, s0, 0x10000
	global_load_lds_dwordx4 v196, s[0:1]
	s_mov_b32 m0, s47
	s_addc_u32 s31, s1, 0
	s_add_i32 s48, s46, 0x4000
	global_load_lds_dwordx4 v198, s[0:1]
	s_mov_b32 m0, s48
	s_add_i32 s65, s46, 0x6000
	global_load_lds_dwordx4 v196, s[30:31]
	s_mov_b32 m0, s65
	s_cmp_eq_u32 s17, 1
	global_load_lds_dwordx4 v198, s[30:31]
	s_cselect_b64 s[30:31], -1, 0
	v_mov_b32_e32 v201, v1
	v_mov_b32_e32 v197, v1
	v_mov_b32_e32 v199, v1
	v_writelane_b32 v255, s30, 2
	v_mov_b32_e32 v249, 0x7f800000
	s_mov_b64 s[36:37], s[80:81]
	s_mov_b32 s7, s18
	v_mov_b32_e32 v248, 1
	v_lshl_add_u64 v[6:7], s[20:21], 0, v[0:1]
	v_lshl_add_u64 v[4:5], s[20:21], 0, v[200:201]
	v_lshl_add_u64 v[2:3], s[0:1], 0, v[196:197]
	v_writelane_b32 v255, s31, 3
	s_cmp_lg_u32 s17, 1
	v_lshl_add_u64 v[8:9], s[0:1], 0, v[198:199]
	s_cbranch_scc1 .LBB0_540
	s_barrier
;     __device__ __forceinline__ const char* abase(const Gemm& g, const Unit& u, size_t tstepA) const { return (const char*)g.A + (size_t)u.pm * tstepA; }
; #define PG8_WAIT_V(n) asm volatile("s_waitcnt vmcnt(" #n ")" ::: "memory")
; template <class Epi, class Sched>
; __device__ __forceinline__ void gemm_phase(LAS unsigned char* lds, const Gemm g, const Sched& S, const Epi& E) {
;     ...
;     const int wid = __builtin_amdgcn_readfirstlane(tid >> 6), lane = tid & 63, wr = wid >> 2, wc = wid & 3, fr = lane & 15, fq = lane >> 4;
;     int K = g.K; asm volatile("" : "+s"(K));
;     const int nt = K / BK;
;     unsigned voffA[2], voffB[2];
; #pragma unroll
;     for (int i = 0; i < 2; ++i) { int R, C; stage_rc(tid * 16 + i * 8192, R, C); const int Rb = Epi::PERM ? ((R & ~31) + perm32(R & 31)) : R;
;         voffA[i] = (unsigned)(R * g.lda + C) * 2u; voffB[i] = (unsigned)(Rb * g.ldb + C) * 2u; }
;     const size_t kstep = (size_t)(BK * 2);
;     const size_t hstepA = (size_t)HALF * g.lda * 2, hstepB = (size_t)HALF * g.ldb * 2;
;     const size_t tstepA = 2 * hstepA, tstepB = 2 * hstepB;
;     const unsigned ldsw = (unsigned)wid * 1024u;
;     const int aoff = lds_byte(wr * 64 + fr, fq * 8), boff = lds_byte(wc * 32 + fr, fq * 8);
;     ...
;     Unit cur, nxt; int ui = 0;
;     if (!S.next(0, cur)) return;
;     Acc acc;
; #pragma unroll
;     for (int a = 0; a < 2; ++a)
; #pragma unroll
;         for (int b = 0; b < 2; ++b)
; #pragma unroll
;             for (int m = 0; m < 4; ++m)
; #pragma unroll
;                 for (int n = 0; n < 2; ++n) acc[a][b][m][n] = (f32x4){0.f, 0.f, 0.f, 0.f};
;     bf16x8 At[4][2], B0[2][2], B1[2][2];
;     const char* cA = S.abase(g, cur, tstepA); const char* cB = S.bbase(g, cur, tstepB);
;     PG8_STAGE(PG8_SB(0, 0), cB, voffB); PG8_STAGE(PG8_SB(0, 1), cB + hstepB, voffB); PG8_STAGE(PG8_SA(0, 0), cA, voffA); PG8_STAGE(PG8_SA(0, 1), cA + hstepA, voffA);
;     if (wr == 1) PG8_BAR;
;     PG8_WAIT_V(2); PG8_BAR;
;     PG8_STAGE(PG8_SB(1, 0), cB + kstep, voffB); PG8_STAGE(PG8_SA(1, 0), cA + kstep, voffA); PG8_STAGE(PG8_SB(1, 1), cB + hstepB + kstep, voffB);
;     PG8_WAIT_V(6); PG8_BAR;
;     for (;;) {
;         const bool has_next = S.next(ui + 1, nxt);
;         const char* nA = has_next ? S.abase(g, nxt, tstepA) : cA; const char* nB = has_next ? S.bbase(g, nxt, tstepB) : cB;
; #pragma unroll 1
;         for (int t = 0; t < nt; t += 2) {
.LBB0_540:
	s_lshl_b32 s30, s76, 8
	s_mov_b32 s18, s76
	s_ashr_i32 s31, s30, 31
	v_readlane_b32 s68, v253, 16
	s_lshl_b64 s[30:31], s[30:31], 2
	v_readlane_b32 s80, v253, 28
	v_readlane_b32 s69, v253, 17
	v_readlane_b32 s70, v253, 18
	v_readlane_b32 s71, v253, 19
	v_readlane_b32 s72, v253, 20
	v_readlane_b32 s73, v253, 21
	v_readlane_b32 s74, v253, 22
	v_readlane_b32 s75, v253, 23
	v_readlane_b32 s76, v253, 24
	v_readlane_b32 s77, v253, 25
	v_readlane_b32 s78, v253, 26
	v_readlane_b32 s79, v253, 27
	v_readlane_b32 s81, v253, 29
	v_readlane_b32 s82, v253, 30
	v_readlane_b32 s83, v253, 31
	s_add_u32 s60, s80, s30
	s_addc_u32 s61, s81, s31
	v_readlane_b32 s68, v253, 32
	v_readlane_b32 s69, v253, 33
	s_add_u32 s88, s68, s30
	v_readlane_b32 s74, v253, 38
	s_addc_u32 s89, s69, s31
	s_ashr_i32 s14, s16, 31
	v_readlane_b32 s77, v253, 41
	s_lshr_b32 s14, s14, 26
	s_lshl_b32 s74, s17, 6
	s_lshl_b32 s25, s17, 13
	s_lshl_b32 s17, s19, 5
	s_add_i32 s14, s16, s14
	s_and_b32 s77, s17, 0x60
	s_add_i32 m0, s46, 0x18000
	v_lshl_add_u64 v[6:7], v[6:7], 0, s[26:27]
	s_ashr_i32 s14, s14, 6
	s_cmpk_lg_i32 s35, 0x100
	s_cselect_b32 s14, s14, 2
	s_lshl_b32 s19, s77, 7
	s_waitcnt vmcnt(2)
	s_barrier
	global_load_lds_dwordx4 v[6:7], off
	v_lshl_add_u64 v[4:5], v[4:5], 0, s[26:27]
	s_add_i32 m0, s46, 0x1a000
	s_add_i32 s96, s46, 0x8000
	s_add_i32 s97, s46, 0xa000
	global_load_lds_dwordx4 v[4:5], off
	v_lshl_add_u64 v[2:3], v[2:3], 0, s[26:27]
	s_mov_b32 m0, s96
	s_add_u32 s30, s20, 0x10080
	global_load_lds_dwordx4 v[2:3], off
	v_lshl_add_u64 v[2:3], v[8:9], 0, s[26:27]
	s_mov_b32 m0, s97
	s_addc_u32 s31, s21, 0
	global_load_lds_dwordx4 v[2:3], off
	s_add_i32 m0, s46, 0x1c000
	v_lshl_add_u64 v[2:3], s[30:31], 0, v[0:1]
	global_load_lds_dwordx4 v[2:3], off
	v_lshl_add_u64 v[2:3], s[30:31], 0, v[200:201]
	s_add_i32 m0, s46, 0x1e000
	v_bfe_u32 v250, v10, 4, 2
	global_load_lds_dwordx4 v[2:3], off
	v_and_b32_e32 v195, 15, v10
	v_lshlrev_b32_e32 v2, 4, v250
	v_lshlrev_b32_e32 v3, 2, v10
	v_lshl_or_b32 v2, v195, 6, v2
	v_and_b32_e32 v3, 32, v3
	v_bitop3_b32 v4, v2, s25, v3 bitop3:0xde
	v_bitop3_b32 v251, v2, s19, v3 bitop3:0xde
	v_lshlrev_b32_e32 v2, 12, v14
	v_and_b32_e32 v2, 0xffffe000, v2
	v_lshl_add_u32 v2, v15, 9, v2
	v_and_b32_e32 v3, 1, v14
	v_lshl_or_b32 v2, v3, 6, v2
	v_lshl_add_u32 v202, v16, 1, v2
	v_lshlrev_b32_e32 v2, 12, v11
	v_readlane_b32 s71, v253, 35
	s_cmp_gt_i32 s16, 63
	v_and_b32_e32 v2, 0xffffe000, v2
	v_readlane_b32 s78, v253, 42
	v_readlane_b32 s79, v253, 43
	s_waitcnt vmcnt(6)
	s_cselect_b64 s[90:91], -1, 0
	s_add_i32 s71, s14, -2
	v_lshl_add_u32 v2, v12, 9, v2
	v_and_b32_e32 v3, 1, v11
	v_readlane_b32 s70, v253, 34
	v_readlane_b32 s73, v253, 37
	v_readlane_b32 s75, v253, 39
	v_readlane_b32 s80, v253, 44
	v_readlane_b32 s81, v253, 45
	v_readlane_b32 s83, v253, 47
	s_cmpk_lt_u32 s15, 0x100
	v_lshl_or_b32 v2, v3, 6, v2
	v_readlane_b32 s78, v254, 58
	s_sext_i32_i8 s17, s24
	s_cselect_b64 s[92:93], -1, 0
	s_ashr_i32 s15, s35, 31
	v_mov_b32_e32 v203, v1
	v_lshl_add_u32 v204, v13, 1, v2
	v_mov_b32_e32 v205, v1
	s_mov_b32 s16, 0
	v_add_u32_e32 v252, 0, v4
	v_readlane_b32 s79, v254, 59
	s_movk_i32 s70, 0x6000
	s_movk_i32 s73, 0x60
	s_movk_i32 s75, 0x5000
	s_movk_i32 s83, 0x600
	s_mov_b64 s[80:81], s[36:37]
	v_readlane_b32 s72, v253, 36
	v_readlane_b32 s76, v253, 40
	v_readlane_b32 s82, v253, 46
	s_barrier
	s_branch .LBB0_543
